# v102 + MLA diagonal (partially masked) tile on a hand-scheduled copy with the causal mask applied to the shifted scores; only tile 0 stays on the compiler path
# baseline (speedup 1.0000x reference)
.LBB0_485:
	s_andn2_b64 vcc, exec, s[40:41]
	s_cbranch_vccnz .LBB0_498
	s_cmp_eq_u32 s30, 0
	s_cbranch_scc1 .Lmla_slow
	s_cmp_le_u32 s31, s4
	s_cbranch_scc1 .Lmla_fast
	s_branch .Lmla_mask

.Lmla_fast_nodma_me:
	s_waitcnt lgkmcnt(0)
	v_mfma_f32_32x32x16_bf16 v[50:65], v[194:197], v[74:77], v[234:249]
	ds_read_b128 v[194:197], v0 offset:6656
	v_add_f32_e32 v254, v202, v203
	v_add_f32_e32 v255, v204, v205
	v_add_f32_e32 v254, v254, v206
	v_add_f32_e32 v255, v255, v207
	v_add_f32_e32 v254, v254, v208
	v_add_f32_e32 v255, v255, v209
	v_mfma_f32_32x32x16_bf16 v[50:65], v[150:153], v[78:81], v[50:65]
	ds_read_b128 v[150:153], v0 offset:6688
	v_add_f32_e32 v254, v254, v210
	v_add_f32_e32 v255, v255, v211
	v_add_f32_e32 v254, v254, v212
	v_add_f32_e32 v255, v255, v213
	v_add_f32_e32 v254, v254, v214
	v_add_f32_e32 v255, v255, v215
	v_mfma_f32_32x32x16_bf16 v[50:65], v[158:161], v[82:85], v[50:65]
	ds_read_b128 v[158:161], v0 offset:6720
	v_add_f32_e32 v254, v254, v216
	v_add_f32_e32 v255, v255, v217
	v_add_f32_e32 v254, v254, v218
	v_add_f32_e32 v255, v255, v219
	v_add_f32_e32 v254, v254, v220
	v_mfma_f32_32x32x16_bf16 v[50:65], v[162:165], v[86:89], v[50:65]
	ds_read_b128 v[162:165], v0 offset:6752
	v_add_f32_e32 v255, v255, v221
	v_add_f32_e32 v254, v254, v222
	v_add_f32_e32 v255, v255, v223
	v_add_f32_e32 v254, v254, v224
	v_add_f32_e32 v255, v255, v225
	v_mfma_f32_32x32x16_bf16 v[50:65], v[174:177], v[90:93], v[50:65]
	ds_read_b128 v[174:177], v0 offset:6784
	v_add_f32_e32 v254, v254, v226
	v_add_f32_e32 v255, v255, v227
	v_add_f32_e32 v254, v254, v228
	v_add_f32_e32 v255, v255, v229
	v_add_f32_e32 v254, v254, v230
	v_mfma_f32_32x32x16_bf16 v[50:65], v[178:181], v[94:97], v[50:65]
	ds_read_b128 v[178:181], v0 offset:6816
	v_add_f32_e32 v255, v255, v231
	v_add_f32_e32 v254, v254, v232
	v_add_f32_e32 v255, v255, v233
	v_add_f32_e32 v254, v254, v255
	v_add_f32_e32 v147, v147, v254
	s_waitcnt lgkmcnt(5)
	v_mfma_f32_32x32x16_bf16 v[34:49], v[194:197], v[74:77], v[234:249]
	ds_read_b64_tr_b16 v[126:127], v142 offset:13312
	ds_read_b64_tr_b16 v[128:129], v142 offset:14848
	ds_read_b64_tr_b16 v[124:125], v142 offset:14912
	ds_read_b64_tr_b16 v[122:123], v142 offset:13376
	s_waitcnt lgkmcnt(8)
	v_mfma_f32_32x32x16_bf16 v[34:49], v[150:153], v[78:81], v[34:49]
	ds_read_b64_tr_b16 v[118:119], v142 offset:16384
	ds_read_b64_tr_b16 v[120:121], v142 offset:17920
	ds_read_b64_tr_b16 v[116:117], v142 offset:17984
	ds_read_b64_tr_b16 v[114:115], v142 offset:16448
	s_waitcnt lgkmcnt(11)
	v_mfma_f32_32x32x16_bf16 v[34:49], v[158:161], v[82:85], v[34:49]
	ds_read_b64_tr_b16 v[110:111], v142 offset:19456
	ds_read_b64_tr_b16 v[112:113], v142 offset:20992
	ds_read_b64_tr_b16 v[108:109], v142 offset:21056
	ds_read_b64_tr_b16 v[106:107], v142 offset:19520
	s_waitcnt lgkmcnt(11)
	v_mfma_f32_32x32x16_bf16 v[34:49], v[162:165], v[86:89], v[34:49]
	ds_read_b64_tr_b16 v[102:103], v142 offset:22528
	ds_read_b64_tr_b16 v[104:105], v142 offset:24064
	ds_read_b64_tr_b16 v[100:101], v142 offset:24128
	ds_read_b64_tr_b16 v[98:99], v142 offset:22592
	v_mfma_f32_32x32x16_bf16 v[34:49], v[174:177], v[90:93], v[34:49]
	v_mfma_f32_32x32x16_bf16 v[34:49], v[178:181], v[94:97], v[34:49]
.Lmla_fast_nostag_me:
	v_cmp_gt_i32_e32 vcc, 0, v146
	v_cndmask_b32_e32 v50, v50, v193, vcc
	v_cmp_gt_i32_e32 vcc, 1, v146
	v_cndmask_b32_e32 v51, v51, v193, vcc
	v_cmp_gt_i32_e32 vcc, 2, v146
	v_cndmask_b32_e32 v52, v52, v193, vcc
	v_cmp_gt_i32_e32 vcc, 3, v146
	v_cndmask_b32_e32 v53, v53, v193, vcc
	v_cmp_gt_i32_e32 vcc, 8, v146
	v_cndmask_b32_e32 v54, v54, v193, vcc
	v_cmp_gt_i32_e32 vcc, 9, v146
	v_cndmask_b32_e32 v55, v55, v193, vcc
	v_cmp_gt_i32_e32 vcc, 10, v146
	v_cndmask_b32_e32 v56, v56, v193, vcc
	v_cmp_gt_i32_e32 vcc, 11, v146
	v_cndmask_b32_e32 v57, v57, v193, vcc
	v_cmp_gt_i32_e32 vcc, 16, v146
	v_cndmask_b32_e32 v58, v58, v193, vcc
	v_cmp_gt_i32_e32 vcc, 17, v146
	v_cndmask_b32_e32 v59, v59, v193, vcc
	v_cmp_gt_i32_e32 vcc, 18, v146
	v_cndmask_b32_e32 v60, v60, v193, vcc
	v_cmp_gt_i32_e32 vcc, 19, v146
	v_cndmask_b32_e32 v61, v61, v193, vcc
	v_cmp_gt_i32_e32 vcc, 24, v146
	v_cndmask_b32_e32 v62, v62, v193, vcc
	v_cmp_gt_i32_e32 vcc, 25, v146
	v_cndmask_b32_e32 v63, v63, v193, vcc
	v_cmp_gt_i32_e32 vcc, 26, v146
	v_cndmask_b32_e32 v64, v64, v193, vcc
	v_cmp_gt_i32_e32 vcc, 27, v146
	v_cndmask_b32_e32 v65, v65, v193, vcc
	v_cmp_gt_i32_e32 vcc, 32, v146
	v_cndmask_b32_e32 v34, v34, v193, vcc
	v_cmp_gt_i32_e32 vcc, 33, v146
	v_cndmask_b32_e32 v35, v35, v193, vcc
	v_cmp_gt_i32_e32 vcc, 34, v146
	v_cndmask_b32_e32 v36, v36, v193, vcc
	v_cmp_gt_i32_e32 vcc, 35, v146
	v_cndmask_b32_e32 v37, v37, v193, vcc
	v_cmp_gt_i32_e32 vcc, 40, v146
	v_cndmask_b32_e32 v38, v38, v193, vcc
	v_cmp_gt_i32_e32 vcc, 41, v146
	v_cndmask_b32_e32 v39, v39, v193, vcc
	v_cmp_gt_i32_e32 vcc, 42, v146
	v_cndmask_b32_e32 v40, v40, v193, vcc
	v_cmp_gt_i32_e32 vcc, 43, v146
	v_cndmask_b32_e32 v41, v41, v193, vcc
	v_cmp_gt_i32_e32 vcc, 48, v146
	v_cndmask_b32_e32 v42, v42, v193, vcc
	v_cmp_gt_i32_e32 vcc, 49, v146
	v_cndmask_b32_e32 v43, v43, v193, vcc
	v_cmp_gt_i32_e32 vcc, 50, v146
	v_cndmask_b32_e32 v44, v44, v193, vcc
	v_cmp_gt_i32_e32 vcc, 51, v146
	v_cndmask_b32_e32 v45, v45, v193, vcc
	v_cmp_gt_i32_e32 vcc, 56, v146
	v_cndmask_b32_e32 v46, v46, v193, vcc
	v_cmp_gt_i32_e32 vcc, 57, v146
	v_cndmask_b32_e32 v47, v47, v193, vcc
	v_cmp_gt_i32_e32 vcc, 58, v146
	v_cndmask_b32_e32 v48, v48, v193, vcc
	v_cmp_gt_i32_e32 vcc, 59, v146
	v_cndmask_b32_e32 v49, v49, v193, vcc
	v_exp_f32_e32 v202, v50
	v_exp_f32_e32 v203, v51
	v_exp_f32_e32 v204, v52
	v_exp_f32_e32 v205, v53
	v_exp_f32_e32 v206, v54
	v_exp_f32_e32 v207, v55
	v_exp_f32_e32 v208, v56
	v_exp_f32_e32 v209, v57
	v_exp_f32_e32 v210, v58
	v_exp_f32_e32 v211, v59
	v_exp_f32_e32 v212, v60
	v_exp_f32_e32 v213, v61
	v_exp_f32_e32 v214, v62
	v_exp_f32_e32 v215, v63
	v_exp_f32_e32 v216, v64
	v_exp_f32_e32 v217, v65
	v_cmp_lt_f32_e32 vcc, 0x44800000, v254
	s_cbranch_vccnz .Lmla_fast_rescale_me
.Lmla_fast_ok_me:
	v_cvt_pk_bf16_f32 v166, v202, v203
	v_cvt_pk_bf16_f32 v167, v204, v205
	v_cvt_pk_bf16_f32 v168, v206, v207
	v_cvt_pk_bf16_f32 v169, v208, v209
	s_waitcnt lgkmcnt(0)
	s_nop 0
	v_mfma_f32_32x32x16_bf16 v[18:33], v[126:129], v[166:169], v[18:33]
	s_add_i32 s8, s30, 1
	s_and_b32 s8, s8, 3
	s_mulk_i32 s8, 0x6400
	v_add3_u32 v0, s8, v143, v132
	v_add3_u32 v142, s8, v144, v145
	v_mfma_f32_32x32x16_bf16 v[2:17], v[122:125], v[166:169], v[2:17]
	v_cvt_pk_bf16_f32 v170, v210, v211
	v_cvt_pk_bf16_f32 v171, v212, v213
	v_cvt_pk_bf16_f32 v172, v214, v215
	v_cvt_pk_bf16_f32 v173, v216, v217
	v_exp_f32_e32 v218, v34
	v_exp_f32_e32 v219, v35
	v_mfma_f32_32x32x16_bf16 v[18:33], v[118:121], v[170:173], v[18:33]
	v_exp_f32_e32 v220, v36
	v_exp_f32_e32 v221, v37
	ds_read_b128 v[194:197], v0
	ds_read_b128 v[150:153], v0 offset:32
	v_mfma_f32_32x32x16_bf16 v[2:17], v[114:117], v[170:173], v[2:17]
	v_exp_f32_e32 v222, v38
	v_exp_f32_e32 v223, v39
	v_exp_f32_e32 v224, v40
	v_exp_f32_e32 v225, v41
	v_cvt_pk_bf16_f32 v166, v218, v219
	v_cvt_pk_bf16_f32 v167, v220, v221
	v_cvt_pk_bf16_f32 v168, v222, v223
	v_cvt_pk_bf16_f32 v169, v224, v225
	ds_read_b128 v[158:161], v0 offset:64
	ds_read_b128 v[162:165], v0 offset:96
	v_mfma_f32_32x32x16_bf16 v[18:33], v[110:113], v[166:169], v[18:33]
	v_exp_f32_e32 v226, v42
	v_exp_f32_e32 v227, v43
	v_exp_f32_e32 v228, v44
	v_mfma_f32_32x32x16_bf16 v[2:17], v[106:109], v[166:169], v[2:17]
	v_exp_f32_e32 v229, v45
	v_exp_f32_e32 v230, v46
	v_exp_f32_e32 v231, v47
	v_exp_f32_e32 v232, v48
	v_exp_f32_e32 v233, v49
	ds_read_b128 v[174:177], v0 offset:128
	ds_read_b128 v[178:181], v0 offset:160
	v_cvt_pk_bf16_f32 v170, v226, v227
	v_cvt_pk_bf16_f32 v171, v228, v229
	v_cvt_pk_bf16_f32 v172, v230, v231
	v_cvt_pk_bf16_f32 v173, v232, v233
	s_add_i32 s30, s30, 1
	s_add_i32 s31, s31, 64
	s_cmp_le_u32 s31, s4
	v_mfma_f32_32x32x16_bf16 v[18:33], v[102:105], v[170:173], v[18:33]
	v_mfma_f32_32x32x16_bf16 v[2:17], v[98:101], v[170:173], v[2:17]
	v_add_f32_e32 v254, v202, v203
	v_add_f32_e32 v255, v204, v205
	v_add_f32_e32 v254, v254, v206
	v_add_f32_e32 v255, v255, v207
	v_add_f32_e32 v254, v254, v208
	v_add_f32_e32 v255, v255, v209
	v_add_f32_e32 v254, v254, v210
	v_add_f32_e32 v255, v255, v211
	v_add_f32_e32 v254, v254, v212
	v_add_f32_e32 v255, v255, v213
	v_add_f32_e32 v254, v254, v214
	v_add_f32_e32 v255, v255, v215
	v_add_f32_e32 v254, v254, v216
	v_add_f32_e32 v255, v255, v217
	v_add_f32_e32 v254, v254, v218
	v_add_f32_e32 v255, v255, v219
	v_add_f32_e32 v254, v254, v220
	v_add_f32_e32 v255, v255, v221
	v_add_f32_e32 v254, v254, v222
	v_add_f32_e32 v255, v255, v223
	v_add_f32_e32 v254, v254, v224
	v_add_f32_e32 v255, v255, v225
	v_add_f32_e32 v254, v254, v226
	v_add_f32_e32 v255, v255, v227
	v_add_f32_e32 v254, v254, v228
	v_add_f32_e32 v255, v255, v229
	v_add_f32_e32 v254, v254, v230
	v_add_f32_e32 v255, v255, v231
	v_add_f32_e32 v254, v254, v232
	v_add_f32_e32 v255, v255, v233
	v_add_f32_e32 v254, v254, v255
	v_add_f32_e32 v147, v147, v254
	v_mov_b64_e32 v[202:203], 0
	v_mov_b64_e32 v[204:205], 0
	v_mov_b64_e32 v[206:207], 0
	v_mov_b64_e32 v[208:209], 0
	v_mov_b64_e32 v[210:211], 0
	v_mov_b64_e32 v[212:213], 0
	v_mov_b64_e32 v[214:215], 0
	v_mov_b64_e32 v[216:217], 0
	v_mov_b64_e32 v[218:219], 0
	v_mov_b64_e32 v[220:221], 0
	v_mov_b64_e32 v[222:223], 0
	v_mov_b64_e32 v[224:225], 0
	v_mov_b64_e32 v[226:227], 0
	v_mov_b64_e32 v[228:229], 0
	v_mov_b64_e32 v[230:231], 0
	v_mov_b64_e32 v[232:233], 0
	s_waitcnt lgkmcnt(0)
	s_branch .Lmla_fast_generic
.Lmla_fast_havek_mo:
.Lmla_fast_nodma_mo:
	s_waitcnt lgkmcnt(0)
	v_mfma_f32_32x32x16_bf16 v[50:65], v[194:197], v[74:77], v[234:249]
	ds_read_b128 v[194:197], v0 offset:6656
	v_add_f32_e32 v254, v202, v203
	v_add_f32_e32 v255, v204, v205
	v_add_f32_e32 v254, v254, v206
	v_add_f32_e32 v255, v255, v207
	v_add_f32_e32 v254, v254, v208
	v_add_f32_e32 v255, v255, v209
	v_mfma_f32_32x32x16_bf16 v[50:65], v[150:153], v[78:81], v[50:65]
	ds_read_b128 v[150:153], v0 offset:6688
	v_add_f32_e32 v254, v254, v210
	v_add_f32_e32 v255, v255, v211
	v_add_f32_e32 v254, v254, v212
	v_add_f32_e32 v255, v255, v213
	v_add_f32_e32 v254, v254, v214
	v_add_f32_e32 v255, v255, v215
	v_mfma_f32_32x32x16_bf16 v[50:65], v[158:161], v[82:85], v[50:65]
	ds_read_b128 v[158:161], v0 offset:6720
	v_add_f32_e32 v254, v254, v216
	v_add_f32_e32 v255, v255, v217
	v_add_f32_e32 v254, v254, v218
	v_add_f32_e32 v255, v255, v219
	v_add_f32_e32 v254, v254, v220
	v_mfma_f32_32x32x16_bf16 v[50:65], v[162:165], v[86:89], v[50:65]
	ds_read_b128 v[162:165], v0 offset:6752
	v_add_f32_e32 v255, v255, v221
	v_add_f32_e32 v254, v254, v222
	v_add_f32_e32 v255, v255, v223
	v_add_f32_e32 v254, v254, v224
	v_add_f32_e32 v255, v255, v225
	v_mfma_f32_32x32x16_bf16 v[50:65], v[174:177], v[90:93], v[50:65]
	ds_read_b128 v[174:177], v0 offset:6784
	v_add_f32_e32 v254, v254, v226
	v_add_f32_e32 v255, v255, v227
	v_add_f32_e32 v254, v254, v228
	v_add_f32_e32 v255, v255, v229
	v_add_f32_e32 v254, v254, v230
	v_mfma_f32_32x32x16_bf16 v[50:65], v[178:181], v[94:97], v[50:65]
	ds_read_b128 v[178:181], v0 offset:6816
	v_add_f32_e32 v255, v255, v231
	v_add_f32_e32 v254, v254, v232
	v_add_f32_e32 v255, v255, v233
	v_add_f32_e32 v254, v254, v255
	v_add_f32_e32 v147, v147, v254
	s_waitcnt lgkmcnt(5)
	v_mfma_f32_32x32x16_bf16 v[34:49], v[194:197], v[74:77], v[234:249]
	ds_read_b64_tr_b16 v[126:127], v142 offset:13312
	ds_read_b64_tr_b16 v[128:129], v142 offset:14848
	ds_read_b64_tr_b16 v[124:125], v142 offset:14912
	ds_read_b64_tr_b16 v[122:123], v142 offset:13376
	s_waitcnt lgkmcnt(8)
	v_mfma_f32_32x32x16_bf16 v[34:49], v[150:153], v[78:81], v[34:49]
	ds_read_b64_tr_b16 v[118:119], v142 offset:16384
	ds_read_b64_tr_b16 v[120:121], v142 offset:17920
	ds_read_b64_tr_b16 v[116:117], v142 offset:17984
	ds_read_b64_tr_b16 v[114:115], v142 offset:16448
	s_waitcnt lgkmcnt(11)
	v_mfma_f32_32x32x16_bf16 v[34:49], v[158:161], v[82:85], v[34:49]
	ds_read_b64_tr_b16 v[110:111], v142 offset:19456
	ds_read_b64_tr_b16 v[112:113], v142 offset:20992
	ds_read_b64_tr_b16 v[108:109], v142 offset:21056
	ds_read_b64_tr_b16 v[106:107], v142 offset:19520
	s_waitcnt lgkmcnt(11)
	v_mfma_f32_32x32x16_bf16 v[34:49], v[162:165], v[86:89], v[34:49]
	ds_read_b64_tr_b16 v[102:103], v142 offset:22528
	ds_read_b64_tr_b16 v[104:105], v142 offset:24064
	ds_read_b64_tr_b16 v[100:101], v142 offset:24128
	ds_read_b64_tr_b16 v[98:99], v142 offset:22592
	v_mfma_f32_32x32x16_bf16 v[34:49], v[174:177], v[90:93], v[34:49]
	v_mfma_f32_32x32x16_bf16 v[34:49], v[178:181], v[94:97], v[34:49]
	s_waitcnt vmcnt(0) lgkmcnt(0)
	s_barrier
